# nt loads also for the P0 x rows / sgu_w copy and the P5 row streams (x, out, residual)
# speedup vs baseline: 1.0408x; 1.0167x over previous
.LBB0_42:
	v_ashrrev_i32_e32 v13, 31, v4
	v_mov_b32_e32 v12, v4
	v_ashrrev_i32_e32 v11, 31, v5
	v_mov_b32_e32 v10, v5
	v_lshl_add_u64 v[14:15], v[12:13], 2, s[22:23]
	v_lshl_add_u64 v[16:17], v[10:11], 2, s[22:23]
	global_load_dword v3, v[14:15], off nt
	global_load_dword v18, v[16:17], off nt
	v_lshrrev_b32_e32 v15, 13, v4
	v_lshrrev_b32_e32 v17, 6, v4
	v_add_u32_e32 v9, -2, v9
	v_lshrrev_b32_e32 v14, 13, v5
	v_lshrrev_b32_e32 v16, 6, v5
	v_and_b32_e32 v15, 1, v15
	v_and_b32_e32 v17, 1, v17
	v_cmp_eq_u32_e32 vcc, 0, v9
	v_and_b32_e32 v14, 1, v14
	v_and_b32_e32 v16, 1, v16
	s_or_b64 s[30:31], vcc, s[30:31]
	v_cmp_le_u32_e32 vcc, v17, v15
	v_cmp_le_u32_e64 s[4:5], v16, v14
	v_add_u32_e32 v5, s17, v5
	v_add_u32_e32 v4, s3, v4
	v_lshl_add_u64 v[12:13], v[12:13], 1, s[28:29]
	v_lshl_add_u64 v[10:11], v[10:11], 1, s[28:29]
	s_waitcnt vmcnt(1)
	v_cndmask_b32_e32 v3, 0, v3, vcc
	s_waitcnt vmcnt(0)
	v_cndmask_b32_e64 v14, 0, v18, s[4:5]
	v_and_b32_sdwa v16, v3, v8 dst_sel:DWORD dst_unused:UNUSED_PAD src0_sel:WORD_1 src1_sel:DWORD
	v_and_b32_sdwa v15, v14, v8 dst_sel:DWORD dst_unused:UNUSED_PAD src0_sel:WORD_1 src1_sel:DWORD
	v_add3_u32 v3, v3, v16, s19
	v_add3_u32 v14, v14, v15, s19
	global_store_short_d16_hi v[12:13], v3, off
	global_store_short_d16_hi v[10:11], v14, off
	s_andn2_b64 exec, exec, s[30:31]
	s_cbranch_execnz .LBB0_42
	s_or_b64 exec, exec, s[30:31]
	v_mad_u64_u32 v[2:3], s[4:5], v7, s24, v[2:3]
	v_cmp_ne_u32_e32 vcc, v6, v7
	s_orn2_b64 s[4:5], vcc, exec

.LBB0_46:
	global_load_dword v3, v[4:5], off nt
	v_bfe_u32 v8, v2, 13, 1
	v_bfe_u32 v9, v2, 6, 1
	v_cmp_le_u32_e32 vcc, v9, v8
	v_add_u32_e32 v2, s24, v2
	v_cmp_lt_i32_e64 s[4:5], s17, v2
	v_lshl_add_u64 v[4:5], v[4:5], 0, s[22:23]
	s_or_b64 s[28:29], s[4:5], s[28:29]
	s_waitcnt vmcnt(0)
	v_cndmask_b32_e32 v3, 0, v3, vcc
	v_bfe_u32 v8, v3, 16, 1
	v_add3_u32 v3, v3, v8, s3
	global_store_short_d16_hi v[6:7], v3, off
	v_lshl_add_u64 v[6:7], v[6:7], 0, s[26:27]
	s_andn2_b64 exec, exec, s[28:29]
	s_cbranch_execnz .LBB0_46

.LBB0_49:
	global_load_dwordx4 v[20:23], v[8:9], off offset:-3072 nt
	global_load_dwordx4 v[24:27], v[8:9], off offset:-2048 nt
	global_load_dwordx4 v[0:3], v[8:9], off nt
	global_load_dwordx4 v[28:31], v[8:9], off offset:-1024 nt
	v_mov_b32_e32 v32, v64
	v_mov_b32_e32 v33, v65
	v_mov_b32_e32 v34, v66
	v_mov_b32_e32 v35, v67
	s_add_i32 s16, s16, s18
	v_lshl_add_u64 v[8:9], v[8:9], 0, s[8:9]
	s_cmpk_lt_i32 s16, 0x4000
	s_waitcnt vmcnt(3)
	v_pk_mul_f32 v[36:37], v[22:23], v[22:23]
	v_pk_mul_f32 v[38:39], v[20:21], v[20:21]
	s_waitcnt vmcnt(2)
	v_pk_mul_f32 v[40:41], v[26:27], v[26:27]
	v_pk_mul_f32 v[42:43], v[24:25], v[24:25]
	v_mov_b32_e32 v48, v20
	v_mov_b32_e32 v49, v22
	s_waitcnt vmcnt(0)
	v_mov_b32_e32 v50, v32
	v_mov_b32_e32 v51, v34
	v_mov_b32_e32 v22, v21
	v_mov_b32_e32 v34, v33
	v_pk_mov_b32 v[20:21], v[38:39], v[36:37] op_sel:[1,0]
	v_mov_b32_e32 v39, v37
	v_pk_mov_b32 v[32:33], v[42:43], v[40:41] op_sel:[1,0]
	v_mov_b32_e32 v43, v41
	v_mul_f32_e32 v45, v1, v1
	v_mul_f32_e32 v47, v2, v2
	v_mul_f32_e32 v44, v29, v29
	v_mul_f32_e32 v46, v31, v31
	v_pk_add_f32 v[20:21], v[20:21], v[38:39]
	v_pk_add_f32 v[32:33], v[32:33], v[42:43]
	v_mul_f32_e32 v19, v0, v0
	v_mul_f32_e32 v52, v3, v3
	v_pk_fma_f32 v[36:37], v[28:29], v[28:29], v[44:45] op_sel_hi:[1,1,0]
	v_pk_fma_f32 v[40:41], v[30:31], v[30:31], v[46:47] op_sel_hi:[1,1,0]
	v_pk_add_f32 v[20:21], v[20:21], v[20:21] op_sel:[0,1] op_sel_hi:[1,0]
	v_pk_add_f32 v[32:33], v[32:33], v[32:33] op_sel:[0,1] op_sel_hi:[1,0]
	v_mov_b32_e32 v37, v47
	v_mov_b32_e32 v41, v52
	v_mov_b32_e32 v21, v19
	v_mov_b32_e32 v33, v45
	v_pk_add_f32 v[36:37], v[36:37], v[40:41]
	v_pk_add_f32 v[20:21], v[20:21], v[32:33]
	s_nop 0
	v_pk_add_f32 v[20:21], v[20:21], v[36:37]
	s_nop 0
	v_add_f32_e32 v19, v20, v21
	ds_bpermute_b32 v20, v10, v19
	s_waitcnt lgkmcnt(0)
	v_add_f32_e32 v19, v19, v20
	ds_bpermute_b32 v20, v11, v19
	s_waitcnt lgkmcnt(0)
	v_add_f32_e32 v19, v19, v20
	ds_bpermute_b32 v20, v12, v19
	s_waitcnt lgkmcnt(0)
	v_add_f32_e32 v19, v19, v20
	ds_bpermute_b32 v20, v13, v19
	s_waitcnt lgkmcnt(0)
	v_add_f32_e32 v19, v19, v20
	ds_bpermute_b32 v20, v14, v19
	s_waitcnt lgkmcnt(0)
	v_add_f32_e32 v19, v19, v20
	ds_bpermute_b32 v20, v15, v19
	s_waitcnt lgkmcnt(0)
	v_add_f32_e32 v19, v19, v20
	v_fmamk_f32 v19, v19, 0x3a800000, v16
	v_mul_f32_e32 v20, 0x4f800000, v19
	v_cmp_gt_f32_e32 vcc, s3, v19
	s_nop 1
	v_cndmask_b32_e32 v19, v19, v20, vcc
	v_sqrt_f32_e32 v20, v19
	s_nop 0
	v_add_u32_e32 v21, -1, v20
	v_add_u32_e32 v32, 1, v20
	v_fma_f32 v33, -v21, v20, v19
	v_fma_f32 v36, -v32, v20, v19
	v_cmp_ge_f32_e64 s[4:5], 0, v33
	s_nop 1
	v_cndmask_b32_e64 v20, v20, v21, s[4:5]
	v_cmp_lt_f32_e64 s[4:5], 0, v36
	s_nop 1
	v_cndmask_b32_e64 v20, v20, v32, s[4:5]
	v_mul_f32_e32 v21, 0x37800000, v20
	v_cndmask_b32_e32 v20, v20, v21, vcc
	v_cmp_class_f32_e32 vcc, v19, v17
	s_nop 1
	v_cndmask_b32_e32 v19, v20, v19, vcc
	v_div_scale_f32 v20, s[4:5], v19, v19, 1.0
	v_rcp_f32_e32 v32, v20
	v_div_scale_f32 v21, vcc, 1.0, v19, 1.0
	v_fma_f32 v33, -v20, v32, 1.0
	v_fmac_f32_e32 v32, v33, v32
	v_mul_f32_e32 v33, v21, v32
	v_fma_f32 v36, -v20, v33, v21
	v_fmac_f32_e32 v33, v36, v32
	v_fma_f32 v20, -v20, v33, v21
	v_div_fmas_f32 v20, v20, v32, v33
	v_div_fixup_f32 v32, v20, v19, 1.0
	v_pk_mul_f32 v[20:21], v[48:49], v[32:33] op_sel_hi:[1,0]
	v_pk_mul_f32 v[22:23], v[22:23], v[32:33] op_sel_hi:[1,0]
	v_pk_mul_f32 v[20:21], v[50:51], v[20:21]
	v_pk_mul_f32 v[22:23], v[34:35], v[22:23]
	v_and_b32_sdwa v19, v21, v18 dst_sel:DWORD dst_unused:UNUSED_PAD src0_sel:WORD_1 src1_sel:DWORD
	v_and_b32_sdwa v34, v23, v18 dst_sel:DWORD dst_unused:UNUSED_PAD src0_sel:WORD_1 src1_sel:DWORD
	v_and_b32_sdwa v35, v22, v18 dst_sel:DWORD dst_unused:UNUSED_PAD src0_sel:WORD_1 src1_sel:DWORD
	v_and_b32_sdwa v33, v20, v18 dst_sel:DWORD dst_unused:UNUSED_PAD src0_sel:WORD_1 src1_sel:DWORD
	v_add3_u32 v19, v21, v19, s10
	v_add3_u32 v21, v23, v34, s10
	v_add3_u32 v22, v22, v35, s10
	v_add3_u32 v20, v20, v33, s10
	v_and_b32_e32 v21, 0xffff0000, v21
	v_and_b32_e32 v22, 0xffff0000, v22
	v_or_b32_sdwa v21, v21, v19 dst_sel:DWORD dst_unused:UNUSED_PAD src0_sel:DWORD src1_sel:WORD_1
	v_or_b32_sdwa v20, v22, v20 dst_sel:DWORD dst_unused:UNUSED_PAD src0_sel:DWORD src1_sel:WORD_1
	global_store_dwordx2 v[6:7], v[20:21], off
	v_mov_b32_e32 v20, v68
	v_mov_b32_e32 v21, v69
	v_mov_b32_e32 v22, v70
	v_mov_b32_e32 v23, v71
	v_mov_b32_e32 v34, v24
	v_mov_b32_e32 v35, v26
	v_mov_b32_e32 v26, v25
	v_pk_mul_f32 v[24:25], v[34:35], v[32:33] op_sel_hi:[1,0]
	v_pk_mul_f32 v[26:27], v[26:27], v[32:33] op_sel_hi:[1,0]
	v_mov_b32_e32 v34, v20
	v_mov_b32_e32 v35, v22
	v_mov_b32_e32 v22, v21
	v_pk_mul_f32 v[20:21], v[34:35], v[24:25]
	v_pk_mul_f32 v[22:23], v[22:23], v[26:27]
	v_and_b32_sdwa v19, v21, v18 dst_sel:DWORD dst_unused:UNUSED_PAD src0_sel:WORD_1 src1_sel:DWORD
	v_and_b32_sdwa v25, v23, v18 dst_sel:DWORD dst_unused:UNUSED_PAD src0_sel:WORD_1 src1_sel:DWORD
	v_and_b32_sdwa v26, v22, v18 dst_sel:DWORD dst_unused:UNUSED_PAD src0_sel:WORD_1 src1_sel:DWORD
	v_and_b32_sdwa v24, v20, v18 dst_sel:DWORD dst_unused:UNUSED_PAD src0_sel:WORD_1 src1_sel:DWORD
	v_add3_u32 v19, v21, v19, s10
	v_add3_u32 v21, v23, v25, s10
	v_add3_u32 v22, v22, v26, s10
	v_add3_u32 v20, v20, v24, s10
	v_and_b32_e32 v21, 0xffff0000, v21
	v_and_b32_e32 v22, 0xffff0000, v22
	v_or_b32_sdwa v21, v21, v19 dst_sel:DWORD dst_unused:UNUSED_PAD src0_sel:DWORD src1_sel:WORD_1
	v_or_b32_sdwa v20, v22, v20 dst_sel:DWORD dst_unused:UNUSED_PAD src0_sel:DWORD src1_sel:WORD_1
	global_store_dwordx2 v[6:7], v[20:21], off offset:512
	v_mov_b32_e32 v20, v72
	v_mov_b32_e32 v21, v73
	v_mov_b32_e32 v22, v74
	v_mov_b32_e32 v23, v75
	v_mov_b32_e32 v24, v28
	v_mov_b32_e32 v25, v30
	v_mov_b32_e32 v30, v29
	v_pk_mul_f32 v[24:25], v[24:25], v[32:33] op_sel_hi:[1,0]
	v_pk_mul_f32 v[26:27], v[30:31], v[32:33] op_sel_hi:[1,0]
	v_mov_b32_e32 v28, v20
	v_mov_b32_e32 v29, v22
	v_mov_b32_e32 v22, v21
	v_pk_mul_f32 v[20:21], v[28:29], v[24:25]
	v_pk_mul_f32 v[22:23], v[22:23], v[26:27]
	v_and_b32_sdwa v19, v21, v18 dst_sel:DWORD dst_unused:UNUSED_PAD src0_sel:WORD_1 src1_sel:DWORD
	v_and_b32_sdwa v25, v23, v18 dst_sel:DWORD dst_unused:UNUSED_PAD src0_sel:WORD_1 src1_sel:DWORD
	v_and_b32_sdwa v26, v22, v18 dst_sel:DWORD dst_unused:UNUSED_PAD src0_sel:WORD_1 src1_sel:DWORD
	v_and_b32_sdwa v24, v20, v18 dst_sel:DWORD dst_unused:UNUSED_PAD src0_sel:WORD_1 src1_sel:DWORD
	v_add3_u32 v19, v21, v19, s10
	v_add3_u32 v21, v23, v25, s10
	v_add3_u32 v22, v22, v26, s10
	v_add3_u32 v20, v20, v24, s10
	v_and_b32_e32 v21, 0xffff0000, v21
	v_and_b32_e32 v22, 0xffff0000, v22
	v_or_b32_sdwa v21, v21, v19 dst_sel:DWORD dst_unused:UNUSED_PAD src0_sel:DWORD src1_sel:WORD_1
	v_or_b32_sdwa v20, v22, v20 dst_sel:DWORD dst_unused:UNUSED_PAD src0_sel:DWORD src1_sel:WORD_1
	global_store_dwordx2 v[6:7], v[20:21], off offset:1024
	v_mov_b32_e32 v20, v76
	v_mov_b32_e32 v21, v77
	v_mov_b32_e32 v22, v78
	v_mov_b32_e32 v23, v79
	v_mov_b32_e32 v24, v0
	v_mov_b32_e32 v25, v2
	v_mov_b32_e32 v2, v1
	v_pk_mul_f32 v[0:1], v[24:25], v[32:33] op_sel_hi:[1,0]
	v_pk_mul_f32 v[2:3], v[2:3], v[32:33] op_sel_hi:[1,0]
	v_mov_b32_e32 v25, v22
	v_mov_b32_e32 v22, v21
	v_mov_b32_e32 v24, v20
	v_pk_mul_f32 v[2:3], v[22:23], v[2:3]
	v_pk_mul_f32 v[0:1], v[24:25], v[0:1]
	v_and_b32_sdwa v21, v3, v18 dst_sel:DWORD dst_unused:UNUSED_PAD src0_sel:WORD_1 src1_sel:DWORD
	v_and_b32_sdwa v22, v2, v18 dst_sel:DWORD dst_unused:UNUSED_PAD src0_sel:WORD_1 src1_sel:DWORD
	v_and_b32_sdwa v19, v1, v18 dst_sel:DWORD dst_unused:UNUSED_PAD src0_sel:WORD_1 src1_sel:DWORD
	v_and_b32_sdwa v20, v0, v18 dst_sel:DWORD dst_unused:UNUSED_PAD src0_sel:WORD_1 src1_sel:DWORD
	v_add3_u32 v3, v3, v21, s10
	v_add3_u32 v2, v2, v22, s10
	v_add3_u32 v0, v0, v20, s10
	v_add3_u32 v1, v1, v19, s10
	v_and_b32_e32 v3, 0xffff0000, v3
	v_and_b32_e32 v2, 0xffff0000, v2
	v_or_b32_sdwa v1, v3, v1 dst_sel:DWORD dst_unused:UNUSED_PAD src0_sel:DWORD src1_sel:WORD_1
	v_or_b32_sdwa v0, v2, v0 dst_sel:DWORD dst_unused:UNUSED_PAD src0_sel:DWORD src1_sel:WORD_1
	global_store_dwordx2 v[6:7], v[0:1], off offset:1536
	v_lshl_add_u64 v[6:7], v[6:7], 0, s[6:7]
	s_cbranch_scc1 .LBB0_49

.LBB0_778:
	s_add_i32 s13, s40, s56
	s_cmpk_lt_i32 s13, 0x4000
	s_cselect_b32 s42, s13, s40
	s_ashr_i32 s41, s40, 31
	s_lshl_b64 s[38:39], s[40:41], 6
	s_add_u32 s44, s8, s38
	s_addc_u32 s45, s9, s39
	global_load_dwordx4 v[18:21], v1, s[44:45] offset:48
	global_load_dwordx4 v[22:25], v1, s[44:45] offset:32
	global_load_dwordx4 v[26:29], v1, s[44:45] offset:16
	global_load_dwordx4 v[30:33], v1, s[44:45]
	s_ashr_i32 s43, s42, 31
	s_lshl_b64 s[38:39], s[42:43], 6
	s_add_u32 s38, s8, s38
	s_addc_u32 s39, s9, s39
	s_lshl_b64 s[46:47], s[40:41], 11
	s_lshl_b64 s[50:51], s[42:43], 11
	v_lshl_add_u64 v[44:45], v[46:47], 0, s[46:47]
	v_lshl_add_u64 v[60:61], v[48:49], 0, s[46:47]
	v_lshl_add_u64 v[42:43], v[46:47], 0, s[50:51]
	v_lshl_add_u64 v[66:67], v[48:49], 0, s[50:51]
	s_lshl_b64 s[44:45], s[40:41], 12
	s_cmpk_gt_i32 s13, 0x3fff
	s_waitcnt vmcnt(0)
	v_add_f32_e32 v22, v22, v23
	v_add_f32_e32 v24, v24, v25
	v_mov_b32_e32 v34, v31
	v_mov_b32_e32 v35, v32
	v_mov_b32_e32 v31, v33
	v_mov_b32_e32 v32, v27
	v_mov_b32_e32 v33, v28
	v_mov_b32_e32 v27, v29
	v_pk_add_f32 v[30:31], v[34:35], v[30:31]
	v_pk_add_f32 v[26:27], v[32:33], v[26:27]
	v_pk_add_f32 v[30:31], v[30:31], v[30:31] op_sel:[0,1] op_sel_hi:[1,0]
	v_pk_add_f32 v[26:27], v[26:27], v[26:27] op_sel:[0,1] op_sel_hi:[1,0]
	v_mov_b32_e32 v31, v18
	v_mov_b32_e32 v27, v19
	v_mov_b32_e32 v23, v20
	v_mov_b32_e32 v25, v21
	v_pk_add_f32 v[18:19], v[30:31], v[26:27]
	v_pk_add_f32 v[20:21], v[22:23], v[24:25]
	s_nop 0
	v_pk_add_f32 v[18:19], v[18:19], v[20:21]
	s_nop 0
	v_add_f32_e32 v0, v18, v19
	v_fmamk_f32 v0, v0, 0x3a800000, v227
	v_cmp_gt_f32_e32 vcc, s7, v0
	v_mul_f32_e32 v18, 0x4f800000, v0
	s_nop 0
	v_cndmask_b32_e32 v0, v0, v18, vcc
	v_sqrt_f32_e32 v34, v0
	global_load_dwordx4 v[18:21], v1, s[38:39] offset:48
	global_load_dwordx4 v[22:25], v1, s[38:39] offset:32
	global_load_dwordx4 v[26:29], v1, s[38:39] offset:16
	global_load_dwordx4 v[30:33], v1, s[38:39]
	v_add_u32_e32 v36, -1, v34
	v_fma_f32 v37, -v36, v34, v0
	v_add_u32_e32 v35, 1, v34
	v_cmp_ge_f32_e64 s[38:39], 0, v37
	s_nop 1
	v_cndmask_b32_e64 v36, v34, v36, s[38:39]
	v_fma_f32 v34, -v35, v34, v0
	v_cmp_lt_f32_e64 s[38:39], 0, v34
	s_nop 1
	v_cndmask_b32_e64 v34, v36, v35, s[38:39]
	v_mul_f32_e32 v35, 0x37800000, v34
	v_cndmask_b32_e32 v34, v34, v35, vcc
	v_cmp_class_f32_e32 vcc, v0, v228
	s_nop 1
	v_cndmask_b32_e32 v0, v34, v0, vcc
	v_div_scale_f32 v34, s[38:39], v0, v0, 1.0
	v_rcp_f32_e32 v35, v34
	s_mov_b64 s[38:39], -1
	v_fma_f32 v36, -v34, v35, 1.0
	v_fmac_f32_e32 v35, v36, v35
	v_div_scale_f32 v36, vcc, 1.0, v0, 1.0
	v_mul_f32_e32 v37, v36, v35
	v_fma_f32 v38, -v34, v37, v36
	v_fmac_f32_e32 v37, v38, v35
	v_fma_f32 v34, -v34, v37, v36
	v_div_fmas_f32 v34, v34, v35, v37
	v_div_fixup_f32 v0, v34, v0, 1.0
	global_load_dwordx2 v[34:35], v[60:61], off nt
	global_load_dwordx2 v[52:53], v[66:67], off nt
	global_load_dwordx2 v[38:39], v[44:45], off nt
	global_load_dwordx2 v[54:55], v[42:43], off nt
	s_waitcnt vmcnt(3)
	v_lshlrev_b32_e32 v36, 16, v34
	s_waitcnt vmcnt(1)
	v_lshlrev_b32_e32 v40, 16, v38
	v_and_b32_e32 v41, 0xffff0000, v38
	v_lshlrev_b32_e32 v38, 16, v39
	v_and_b32_e32 v39, 0xffff0000, v39
	v_and_b32_e32 v37, 0xffff0000, v34
	v_lshlrev_b32_e32 v34, 16, v35
	v_and_b32_e32 v35, 0xffff0000, v35
	v_pk_mul_f32 v[56:57], v[0:1], v[40:41] op_sel_hi:[0,1]
	v_pk_mul_f32 v[38:39], v[0:1], v[38:39] op_sel_hi:[0,1]
	v_pk_fma_f32 v[40:41], v[4:5], v[38:39], v[34:35]
	v_pk_fma_f32 v[38:39], v[2:3], v[56:57], v[36:37]
	global_load_dwordx2 v[34:35], v[60:61], off offset:512 nt
	global_load_dwordx2 v[56:57], v[66:67], off offset:512 nt
	global_load_dwordx2 v[36:37], v[44:45], off offset:512 nt
	global_load_dwordx2 v[58:59], v[42:43], off offset:512 nt
	s_waitcnt vmcnt(3)
	v_lshlrev_b32_e32 v62, 16, v34
	s_waitcnt vmcnt(1)
	v_lshlrev_b32_e32 v64, 16, v36
	v_and_b32_e32 v65, 0xffff0000, v36
	v_lshlrev_b32_e32 v36, 16, v37
	v_and_b32_e32 v37, 0xffff0000, v37
	v_and_b32_e32 v63, 0xffff0000, v34
	v_lshlrev_b32_e32 v34, 16, v35
	v_and_b32_e32 v35, 0xffff0000, v35
	v_pk_mul_f32 v[64:65], v[0:1], v[64:65] op_sel_hi:[0,1]
	v_pk_mul_f32 v[36:37], v[0:1], v[36:37] op_sel_hi:[0,1]
	v_pk_fma_f32 v[36:37], v[8:9], v[36:37], v[34:35]
	v_pk_fma_f32 v[34:35], v[6:7], v[64:65], v[62:63]
	global_load_dwordx2 v[74:75], v[60:61], off offset:1024 nt
	global_load_dwordx2 v[62:63], v[66:67], off offset:1024 nt
	global_load_dwordx2 v[72:73], v[44:45], off offset:1024 nt
	global_load_dwordx2 v[64:65], v[42:43], off offset:1024 nt
	global_load_dwordx2 v[70:71], v[60:61], off offset:1536 nt
	s_nop 0
	global_load_dwordx2 v[66:67], v[66:67], off offset:1536 nt
	s_nop 0
	global_load_dwordx2 v[44:45], v[44:45], off offset:1536 nt
	s_nop 0
	global_load_dwordx2 v[68:69], v[42:43], off offset:1536 nt
	v_lshl_add_u64 v[60:61], v[50:51], 0, s[44:45]
	global_store_dwordx4 v[60:61], v[38:41], off sc1
	s_cbranch_scc0 .LBB0_780
	global_store_dwordx4 v[60:61], v[34:37], off offset:1024 sc1
	s_mov_b64 s[38:39], 0

.LBB0_783:
	s_andn2_b64 vcc, exec, s[38:39]
	s_cbranch_vccnz .LBB0_803
	v_mov_b32_e32 v0, v224
	s_nop 0
	v_readfirstlane_b32 s8, v0
	s_ashr_i32 s16, s8, 6
	v_readlane_b32 s8, v241, 47
	s_add_i32 s8, s16, s8
	s_cmpk_gt_i32 s8, 0x3fff
	s_cbranch_scc1 .LBB0_803
	s_load_dwordx2 s[38:39], s[28:29], 0x10
	s_load_dwordx4 s[40:43], s[28:29], 0x0
	v_and_b32_e32 v34, 63, v0
	v_lshlrev_b32_e32 v0, 4, v34
	s_mov_b64 s[28:29], 0x1000
	s_waitcnt lgkmcnt(0)
	global_load_dwordx4 v[2:5], v0, s[38:39]
	global_load_dwordx4 v[6:9], v0, s[38:39] offset:1024
	global_load_dwordx4 v[10:13], v0, s[38:39] offset:2048
	global_load_dwordx4 v[14:17], v0, s[38:39] offset:3072
	v_lshl_add_u64 v[26:27], s[42:43], 0, v[0:1]
	v_add_co_u32_e32 v30, vcc, s91, v26
	v_lshl_add_u64 v[28:29], v[26:27], 0, s[28:29]
	s_nop 0
	v_addc_co_u32_e32 v31, vcc, 0, v27, vcc
	global_load_dwordx4 v[18:21], v[28:29], off offset:2048 nt
	global_load_dwordx4 v[22:25], v[28:29], off offset:1024 nt
	s_nop 0
	global_load_dwordx4 v[26:29], v[28:29], off offset:3072 nt
	s_nop 0
	global_load_dwordx4 v[30:33], v[30:31], off nt
	v_lshlrev_b32_e32 v34, 3, v34
	v_mov_b32_e32 v35, v1
	v_lshl_add_u64 v[36:37], s[26:27], 0, v[34:35]
	s_mov_b64 s[28:29], 0x8000000
	v_lshl_add_u64 v[58:59], v[36:37], 0, s[28:29]
	s_mov_b64 s[28:29], 0xe000000
	s_add_u32 s9, s26, 0x2700000
	v_lshl_add_u64 v[62:63], v[36:37], 0, s[28:29]
	s_mov_b64 s[28:29], 0x3000000
	s_addc_u32 s13, s27, 0
	v_lshl_add_u64 v[64:65], v[36:37], 0, s[28:29]
	s_ashr_i32 s25, s16, 31
	v_readlane_b32 s28, v241, 47
	s_add_u32 s28, s28, s16
	v_readlane_b32 s16, v241, 48
	s_addc_u32 s29, s16, s25
	s_lshl_b64 s[38:39], s[28:29], 12
	s_add_u32 s38, s40, s38
	s_addc_u32 s39, s41, s39
	v_lshl_add_u64 v[66:67], s[38:39], 0, v[0:1]
	s_lshl_b64 s[38:39], s[28:29], 11
	v_lshl_add_u64 v[60:61], s[40:41], 0, v[0:1]
	s_waitcnt vmcnt(0)
	v_or_b32_e32 v68, s38, v34
	v_mov_b32_e32 v69, s39
	s_lshl_b64 s[28:29], s[28:29], 6
	s_branch .LBB0_787

.LBB0_787:
	s_add_i32 s16, s56, s8
	s_cmpk_lt_i32 s16, 0x4000
	s_cselect_b64 s[44:45], -1, 0
	s_and_b64 s[38:39], s[44:45], exec
	s_cselect_b32 s42, s16, s8
	s_add_u32 s40, s26, s28
	s_addc_u32 s41, s27, s29
	s_add_u32 s46, s40, 0x2700000
	s_addc_u32 s47, s41, 0
	s_ashr_i32 s43, s42, 31
	s_lshl_b64 s[38:39], s[42:43], 6
	s_add_u32 s38, s9, s38
	s_addc_u32 s39, s13, s39
	global_load_dwordx4 v[34:37], v1, s[46:47] offset:48
	global_load_dwordx4 v[38:41], v1, s[46:47] offset:32
	global_load_dwordx4 v[42:45], v1, s[46:47] offset:16
	global_load_dwordx4 v[46:49], v229, s[40:41]
	global_load_dwordx4 v[50:53], v1, s[38:39] offset:48
	global_load_dwordx4 v[54:57], v1, s[38:39] offset:32
	global_load_dwordx4 v[70:73], v1, s[38:39] offset:16
	global_load_dwordx4 v[74:77], v1, s[38:39]
	s_lshl_b64 s[46:47], s[42:43], 11
	s_lshl_b64 s[50:51], s[42:43], 12
	s_cmpk_gt_i32 s16, 0x3fff
	s_brev_b32 s16, 16
	v_lshl_add_u64 v[90:91], v[58:59], 0, s[46:47]
	v_lshl_add_u64 v[84:85], v[60:61], 0, s[50:51]
	s_waitcnt vmcnt(6)
	v_add_f32_e32 v38, v38, v39
	v_add_f32_e32 v40, v40, v41
	s_waitcnt vmcnt(4)
	v_mov_b32_e32 v78, v47
	v_mov_b32_e32 v79, v48
	v_mov_b32_e32 v47, v49
	v_mov_b32_e32 v48, v43
	v_mov_b32_e32 v49, v44
	v_mov_b32_e32 v43, v45
	v_pk_add_f32 v[46:47], v[78:79], v[46:47]
	v_pk_add_f32 v[42:43], v[48:49], v[42:43]
	v_pk_add_f32 v[46:47], v[46:47], v[46:47] op_sel:[0,1] op_sel_hi:[1,0]
	v_pk_add_f32 v[42:43], v[42:43], v[42:43] op_sel:[0,1] op_sel_hi:[1,0]
	v_mov_b32_e32 v47, v34
	v_mov_b32_e32 v43, v35
	v_mov_b32_e32 v39, v36
	v_mov_b32_e32 v41, v37
	v_pk_add_f32 v[34:35], v[46:47], v[42:43]
	v_pk_add_f32 v[36:37], v[38:39], v[40:41]
	s_waitcnt vmcnt(2)
	v_add_f32_e32 v38, v54, v55
	v_pk_add_f32 v[34:35], v[34:35], v[36:37]
	s_waitcnt vmcnt(1)
	v_mov_b32_e32 v36, v71
	v_add_f32_e32 v0, v34, v35
	s_waitcnt vmcnt(0)
	v_mov_b32_e32 v34, v75
	v_mov_b32_e32 v35, v76
	v_mov_b32_e32 v75, v77
	v_mov_b32_e32 v37, v72
	v_mov_b32_e32 v71, v73
	v_pk_add_f32 v[34:35], v[34:35], v[74:75]
	v_pk_add_f32 v[36:37], v[36:37], v[70:71]
	v_pk_add_f32 v[34:35], v[34:35], v[34:35] op_sel:[0,1] op_sel_hi:[1,0]
	v_pk_add_f32 v[36:37], v[36:37], v[36:37] op_sel:[0,1] op_sel_hi:[1,0]
	v_add_f32_e32 v40, v56, v57
	v_mov_b32_e32 v35, v50
	v_mov_b32_e32 v37, v51
	v_mov_b32_e32 v39, v52
	v_mov_b32_e32 v41, v53
	v_pk_add_f32 v[34:35], v[34:35], v[36:37]
	v_pk_add_f32 v[36:37], v[38:39], v[40:41]
	v_fmamk_f32 v0, v0, 0x3a800000, v227
	v_pk_add_f32 v[34:35], v[34:35], v[36:37]
	v_cmp_gt_f32_e32 vcc, s7, v0
	v_add_f32_e32 v34, v34, v35
	v_mul_f32_e32 v35, 0x4f800000, v0
	v_cndmask_b32_e32 v0, v0, v35, vcc
	v_sqrt_f32_e32 v35, v0
	v_fmamk_f32 v34, v34, 0x3a800000, v227
	v_cmp_gt_f32_e64 s[38:39], s7, v34
	v_mul_f32_e32 v38, 0x4f800000, v34
	v_add_u32_e32 v37, -1, v35
	v_fma_f32 v41, -v37, v35, v0
	v_add_u32_e32 v36, 1, v35
	v_cmp_ge_f32_e64 s[40:41], 0, v41
	v_cndmask_b32_e64 v34, v34, v38, s[38:39]
	v_sqrt_f32_e32 v38, v34
	v_cndmask_b32_e64 v37, v35, v37, s[40:41]
	v_fma_f32 v35, -v36, v35, v0
	v_cmp_lt_f32_e64 s[40:41], 0, v35
	v_add_u32_e32 v40, -1, v38
	v_add_u32_e32 v39, 1, v38
	v_cndmask_b32_e64 v35, v37, v36, s[40:41]
	v_mul_f32_e32 v36, 0x37800000, v35
	v_cndmask_b32_e32 v35, v35, v36, vcc
	v_cmp_class_f32_e32 vcc, v0, v228
	v_lshl_add_u64 v[70:71], s[26:27], 0, v[68:69]
	s_nop 0
	v_cndmask_b32_e32 v0, v35, v0, vcc
	v_div_scale_f32 v35, s[40:41], v0, v0, 1.0
	v_rcp_f32_e32 v36, v35
	s_nop 0
	v_fma_f32 v37, -v35, v36, 1.0
	v_fmac_f32_e32 v36, v37, v36
	v_div_scale_f32 v37, vcc, 1.0, v0, 1.0
	v_mul_f32_e32 v41, v37, v36
	v_fma_f32 v42, -v35, v41, v37
	v_fmac_f32_e32 v41, v42, v36
	v_fma_f32 v35, -v35, v41, v37
	v_div_fmas_f32 v35, v35, v36, v41
	v_div_fixup_f32 v80, v35, v0, 1.0
	v_fma_f32 v0, -v40, v38, v34
	v_cmp_ge_f32_e32 vcc, 0, v0
	v_fma_f32 v35, -v39, v38, v34
	s_nop 0
	v_cndmask_b32_e32 v0, v38, v40, vcc
	v_cmp_lt_f32_e32 vcc, 0, v35
	s_nop 1
	v_cndmask_b32_e32 v0, v0, v39, vcc
	v_mul_f32_e32 v35, 0x37800000, v0
	v_cndmask_b32_e64 v0, v0, v35, s[38:39]
	v_cmp_class_f32_e32 vcc, v34, v228
	s_nop 1
	v_cndmask_b32_e32 v0, v0, v34, vcc
	v_div_scale_f32 v34, s[38:39], v0, v0, 1.0
	v_rcp_f32_e32 v35, v34
	s_nop 0
	v_fma_f32 v36, -v34, v35, 1.0
	v_fmac_f32_e32 v35, v36, v35
	v_div_scale_f32 v36, vcc, 1.0, v0, 1.0
	v_mul_f32_e32 v37, v36, v35
	v_fma_f32 v38, -v34, v37, v36
	v_fmac_f32_e32 v37, v38, v35
	v_fma_f32 v34, -v34, v37, v36
	v_div_fmas_f32 v34, v34, v35, v37
	v_add_co_u32_e32 v96, vcc, s16, v70
	v_div_fixup_f32 v82, v34, v0, 1.0
	s_nop 0
	v_addc_co_u32_e32 v97, vcc, 0, v71, vcc
	global_load_dwordx4 v[34:37], v[66:67], off nt
	global_load_dwordx4 v[38:41], v[84:85], off nt
	global_load_dwordx2 v[42:43], v[96:97], off nt
	global_load_dwordx2 v[44:45], v[90:91], off nt
	v_add_co_u32_e32 v102, vcc, 0xe000000, v70
	s_waitcnt vmcnt(1)
	v_lshlrev_b32_e32 v46, 16, v42
	v_and_b32_e32 v47, 0xffff0000, v42
	v_lshlrev_b32_e32 v42, 16, v43
	v_and_b32_e32 v43, 0xffff0000, v43
	s_waitcnt vmcnt(0)
	v_lshlrev_b32_e32 v48, 16, v44
	v_and_b32_e32 v49, 0xffff0000, v44
	v_lshlrev_b32_e32 v44, 16, v45
	v_and_b32_e32 v45, 0xffff0000, v45
	v_pk_mul_f32 v[46:47], v[80:81], v[46:47] op_sel_hi:[0,1]
	v_pk_mul_f32 v[42:43], v[80:81], v[42:43] op_sel_hi:[0,1]
	v_pk_fma_f32 v[76:77], v[4:5], v[42:43], v[36:37]
	v_pk_fma_f32 v[78:79], v[2:3], v[46:47], v[34:35]
	v_pk_mul_f32 v[34:35], v[82:83], v[48:49] op_sel_hi:[0,1]
	v_pk_mul_f32 v[36:37], v[82:83], v[44:45] op_sel_hi:[0,1]
	v_pk_fma_f32 v[72:73], v[4:5], v[36:37], v[40:41]
	v_pk_fma_f32 v[74:75], v[2:3], v[34:35], v[38:39]
	global_load_dwordx4 v[54:57], v[66:67], off offset:1024 nt
	global_load_dwordx4 v[50:53], v[84:85], off offset:1024 nt
	global_load_dwordx2 v[94:95], v[96:97], off offset:512 nt
	global_load_dwordx2 v[92:93], v[90:91], off offset:512 nt
	global_load_dwordx4 v[46:49], v[66:67], off offset:2048 nt
	global_load_dwordx4 v[42:45], v[84:85], off offset:2048 nt
	global_load_dwordx2 v[88:89], v[96:97], off offset:1024 nt
	global_load_dwordx2 v[86:87], v[90:91], off offset:1024 nt
	global_load_dwordx4 v[38:41], v[66:67], off offset:3072 nt
	global_load_dwordx4 v[34:37], v[84:85], off offset:3072 nt
	s_nop 0
	global_load_dwordx2 v[84:85], v[96:97], off offset:1536 nt
	s_nop 0
	global_load_dwordx2 v[90:91], v[90:91], off offset:1536 nt
	v_lshl_add_u64 v[96:97], v[62:63], 0, s[46:47]
	v_addc_co_u32_e32 v103, vcc, 0, v71, vcc
	v_cvt_pk_bf16_f32 v100, v78, v79
	v_cvt_pk_bf16_f32 v101, v76, v77
	v_cvt_pk_bf16_f32 v98, v74, v75
	v_cvt_pk_bf16_f32 v99, v72, v73
	global_store_dwordx2 v[102:103], v[100:101], off
	s_cbranch_scc1 .LBB0_789
	global_store_dwordx2 v[96:97], v[98:99], off
